# v16 + same software-pipelined norm for norm1 phase of layers 1-3
# speedup vs baseline: 1.0296x; 1.0050x over previous
; __device__ __forceinline__ int opaque_tid() { int t = threadIdx.x; asm volatile("" : "+v"(t)); return t; }
; __device__ __forceinline__ unsigned pk2(float lo, float hi) { f32x2_t v = {lo, hi}; bf16x2_t b = __builtin_convertvector(v, bf16x2_t); return __builtin_bit_cast(unsigned, b); }
; __device__ __forceinline__ void phase_norm(const Params& P, int l, int which, bool first) {
;     const int tid = opaque_tid(), lane = tid & 63, wave = tid >> 6;
;     const int gw = blockIdx.x * 8 + wave, NGW = gridDim.x * 8;
;     const float* gain = (which == 0 ? P.norm1 : P.norm2) + (size_t)l * DM;
;     const float* mod = (const float*)(P.ws + WS_MOD) + (size_t)l * 17 * MODW + (which == 0 ? 0 : 3 * DM);
;     bf16_t* H = (bf16_t*)(P.ws + WS_H);
;     for (int r = gw; r < ROWS; r += NGW) {
;         const int b = r / TT, t = r - b * TT; const int bb = (t < CTX) ? 16 : b;
;         float* xr = xrow_ptr(P, r);
;         const float* src = first ? ((t < CTX) ? P.ctx + ((size_t)b * CTX + t) * DM : P.x + ((size_t)b * SEQ + (t - CTX)) * DM) : xr;
;         f32x4 v[4]; float s2 = 0.f;
; #pragma unroll
;         for (int j = 0; j < 4; ++j) { v[j] = *((const f32x4*)src + lane + 64 * j); s2 += (v[j].x * v[j].x + v[j].y * v[j].y) + (v[j].z * v[j].z + v[j].w * v[j].w); }
;         if (first) {
; #pragma unroll
;             for (int j = 0; j < 4; ++j) *((f32x4*)xr + lane + 64 * j) = v[j];
;         }
;         const float rstd = 1.0f / sqrtf(wave_sum(s2, lane) * (1.0f / DM) + RMS_EPS);
;         const float* mrow = mod + (size_t)bb * MODW;
; #pragma unroll
;         for (int j = 0; j < 4; ++j) {
;             const int c0 = 4 * (lane + 64 * j);
;             const f32x4 g = *(const f32x4*)(gain + c0), sh = *(const f32x4*)(mrow + c0), scl = *(const f32x4*)(mrow + DM + c0);
;             const f32x4 y = v[j] * rstd * g * (scl + 1.0f) + sh;
;             u32x2 w; w.x = pk2(y.x, y.y); w.y = pk2(y.z, y.w);
;             *(u32x2*)(H + (size_t)r * DM + c0) = w;
;         }
;     }
; __global__ void __launch_bounds__(512, 2) hybrid_fwd(Params Parg) {
;     ...
;     for (int l = 0; l < DEPTH; ++l) {
;         const bool lat_only = (l == DEPTH - 1);
;         { const Params P = fresh_params(); phase_norm(P, l, 0, l == 0); if (l == 0) convert_weights(P, 0, lds, 0); }
.LBB0_64:
	s_mov_b64 s[38:39], s[28:29]
	s_load_dwordx4 s[44:47], s[38:39], 0x30
	s_load_dwordx2 s[10:11], s[38:39], 0x70
	s_load_dwordx4 s[52:55], s[38:39], 0x80
	s_load_dwordx4 s[56:59], s[38:39], 0x98
	v_mov_b32_e32 v0, v200
	v_readlane_b32 s0, v253, 62
	v_ashrrev_i32_e32 v1, 6, v0
	s_mov_b32 s9, s65
	s_cmp_eq_u32 s8, 0
	v_add_u32_e32 v16, s0, v1
	s_mul_hi_u32 s0, s8, 0x66000
	v_writelane_b32 v255, s8, 0
	v_writelane_b32 v254, s0, 63
	s_mul_i32 s0, s8, 0x66000
	v_writelane_b32 v255, s9, 1
	v_writelane_b32 v255, s0, 2
	s_mov_b32 s0, 0x9000
	v_cmp_gt_i32_e32 vcc, s0, v16
	s_cselect_b64 s[0:1], -1, 0
	v_cndmask_b32_e64 v38, 0, 1, s[0:1]
	s_and_saveexec_b64 s[24:25], vcc
	s_cbranch_execz .LBB0_75
	v_readlane_b32 s8, v255, 0
	s_nop 1
	s_cmp_eq_u32 s8, 0
	s_cbranch_scc1 .Lnf_n1_orig
	v_readlane_b32 s8, v255, 2
	v_readlane_b32 s9, v254, 63
	v_readlane_b32 s100, v255, 0
	v_readfirstlane_b32 s101, v16
	v_and_b32_e32 v120, 63, v200
	v_lshlrev_b32_e32 v121, 3, v120
	v_lshlrev_b32_e32 v32, 2, v120
	v_xor_b32_e32 v122, 4, v32
	v_xor_b32_e32 v123, 8, v32
	v_xor_b32_e32 v124, 16, v32
	v_xor_b32_e32 v125, 32, v32
	v_xor_b32_e32 v126, 64, v32
	v_xor_b32_e32 v127, 0x80, v32
	v_lshlrev_b32_e32 v120, 4, v120
	s_waitcnt lgkmcnt(0)
	s_add_u32 s8, s58, s8
	s_addc_u32 s9, s59, s9
	s_add_u32 s50, s8, 0x101000
	s_addc_u32 s51, s9, 0
	s_lshl_b32 s100, s100, 12
	s_add_u32 s12, s44, s100
	s_addc_u32 s13, s45, 0
	s_add_u32 s36, s58, 0x4500000
	s_addc_u32 s37, s59, 0
	global_load_dwordx4 v[162:165], v120, s[12:13]
	global_load_dwordx4 v[166:169], v120, s[12:13] offset:1024
	global_load_dwordx4 v[170:173], v120, s[12:13] offset:2048
	global_load_dwordx4 v[174:177], v120, s[12:13] offset:3072
	s_lshr_b32 s8, s101, 8
	s_mul_i32 s8, s8, 57
	s_lshr_b32 s8, s8, 9
	s_mul_i32 s9, s8, 0x900
	s_sub_u32 s9, s101, s9
	s_lshl_b32 s12, s8, 11
	s_add_u32 s12, s12, s9
	s_sub_u32 s12, s12, 0x100
	s_lshl_b32 s8, s8, 8
	s_add_u32 s8, s8, s9
	s_cmp_lt_u32 s9, 0x100
	s_cselect_b32 s8, s8, s12
	s_cselect_b32 s12, s36, s56
	s_cselect_b32 s13, s37, s57
	s_lshl_b32 s8, s8, 12
	s_add_u32 s12, s12, s8
	s_addc_u32 s13, s13, 0
	global_load_dwordx4 v[0:3], v120, s[12:13]
	global_load_dwordx4 v[4:7], v120, s[12:13] offset:1024
	global_load_dwordx4 v[8:11], v120, s[12:13] offset:2048
	global_load_dwordx4 v[12:15], v120, s[12:13] offset:3072
	s_add_u32 s100, s101, s68
	s_cmp_le_u32 s100, s71
	s_cselect_b32 s100, s100, s101
	s_lshr_b32 s8, s100, 8
	s_mul_i32 s8, s8, 57
	s_lshr_b32 s8, s8, 9
	s_mul_i32 s9, s8, 0x900
	s_sub_u32 s9, s100, s9
	s_lshl_b32 s12, s8, 11
	s_add_u32 s12, s12, s9
	s_sub_u32 s12, s12, 0x100
	s_lshl_b32 s8, s8, 8
	s_add_u32 s8, s8, s9
	s_cmp_lt_u32 s9, 0x100
	s_cselect_b32 s8, s8, s12
	s_cselect_b32 s12, s36, s56
	s_cselect_b32 s13, s37, s57
	s_lshl_b32 s8, s8, 12
	s_add_u32 s12, s12, s8
	s_addc_u32 s13, s13, 0
	global_load_dwordx4 v[16:19], v120, s[12:13]
	global_load_dwordx4 v[20:23], v120, s[12:13] offset:1024
	global_load_dwordx4 v[24:27], v120, s[12:13] offset:2048
	global_load_dwordx4 v[28:31], v120, s[12:13] offset:3072
	s_mul_i32 s100, s68, 2
	s_add_u32 s100, s100, s101
	s_cmp_le_u32 s100, s71
	s_cselect_b32 s100, s100, s101
	s_lshr_b32 s8, s100, 8
	s_mul_i32 s8, s8, 57
	s_lshr_b32 s8, s8, 9
	s_mul_i32 s9, s8, 0x900
	s_sub_u32 s9, s100, s9
	s_lshl_b32 s12, s8, 11
	s_add_u32 s12, s12, s9
	s_sub_u32 s12, s12, 0x100
	s_lshl_b32 s8, s8, 8
	s_add_u32 s8, s8, s9
	s_cmp_lt_u32 s9, 0x100
	s_cselect_b32 s8, s8, s12
	s_cselect_b32 s12, s36, s56
	s_cselect_b32 s13, s37, s57
	s_lshl_b32 s8, s8, 12
	s_add_u32 s12, s12, s8
	s_addc_u32 s13, s13, 0
	global_load_dwordx4 v[40:43], v120, s[12:13]
	global_load_dwordx4 v[44:47], v120, s[12:13] offset:1024
	global_load_dwordx4 v[48:51], v120, s[12:13] offset:2048
	global_load_dwordx4 v[52:55], v120, s[12:13] offset:3072
	s_lshr_b32 s8, s101, 8
	s_mul_i32 s8, s8, 57
	s_lshr_b32 s8, s8, 9
	s_mul_i32 s9, s8, 0x900
	s_sub_u32 s9, s101, s9
	s_cmp_lt_u32 s9, 0x100
	s_cselect_b32 s8, 16, s8
	s_mul_i32 s8, s8, 0x6000
	s_add_u32 s12, s50, s8
	s_addc_u32 s13, s51, 0
	global_load_dwordx4 v[56:59], v120, s[12:13] offset:-4096
	global_load_dwordx4 v[60:63], v120, s[12:13] offset:-3072
	global_load_dwordx4 v[64:67], v120, s[12:13] offset:-2048
	global_load_dwordx4 v[68:71], v120, s[12:13] offset:-1024
	global_load_dwordx4 v[72:75], v120, s[12:13]
	global_load_dwordx4 v[76:79], v120, s[12:13] offset:1024
	global_load_dwordx4 v[80:83], v120, s[12:13] offset:2048
	global_load_dwordx4 v[84:87], v120, s[12:13] offset:3072
	s_waitcnt vmcnt(16)
	s_add_u32 s100, s101, s68
	s_cmp_le_u32 s100, s71
	s_cselect_b32 s100, s100, s101
	s_lshr_b32 s8, s100, 8
	s_mul_i32 s8, s8, 57
	s_lshr_b32 s8, s8, 9
	s_mul_i32 s9, s8, 0x900
	s_sub_u32 s9, s100, s9
	s_cmp_lt_u32 s9, 0x100
	s_cselect_b32 s8, 16, s8
	s_mul_i32 s8, s8, 0x6000
	s_add_u32 s12, s50, s8
	s_addc_u32 s13, s51, 0
	global_load_dwordx4 v[88:91], v120, s[12:13] offset:-4096
	global_load_dwordx4 v[92:95], v120, s[12:13] offset:-3072
	global_load_dwordx4 v[96:99], v120, s[12:13] offset:-2048
	global_load_dwordx4 v[100:103], v120, s[12:13] offset:-1024
	global_load_dwordx4 v[104:107], v120, s[12:13]
	global_load_dwordx4 v[108:111], v120, s[12:13] offset:1024
	global_load_dwordx4 v[112:115], v120, s[12:13] offset:2048
	global_load_dwordx4 v[116:119], v120, s[12:13] offset:3072
	v_mul_f32_e32 v32, v1, v1
	v_mul_f32_e32 v33, v3, v3
	v_fmac_f32_e32 v32, v0, v0
	v_fmac_f32_e32 v33, v2, v2
	v_add_f32_e32 v34, v32, v33
	v_mul_f32_e32 v32, v5, v5
	v_mul_f32_e32 v33, v7, v7
	v_fmac_f32_e32 v32, v4, v4
	v_fmac_f32_e32 v33, v6, v6
	v_add_f32_e32 v32, v32, v33
	v_add_f32_e32 v34, v34, v32
	v_mul_f32_e32 v32, v9, v9
	v_mul_f32_e32 v33, v11, v11
	v_fmac_f32_e32 v32, v8, v8
	v_fmac_f32_e32 v33, v10, v10
	v_add_f32_e32 v32, v32, v33
	v_add_f32_e32 v34, v34, v32
	v_mul_f32_e32 v32, v13, v13
	v_mul_f32_e32 v33, v15, v15
	v_fmac_f32_e32 v32, v12, v12
	v_fmac_f32_e32 v33, v14, v14
	v_add_f32_e32 v32, v32, v33
	v_add_f32_e32 v34, v34, v32
	ds_bpermute_b32 v32, v122, v34
	s_waitcnt lgkmcnt(0)
; __device__ __forceinline__ unsigned pk2(float lo, float hi) { f32x2_t v = {lo, hi}; bf16x2_t b = __builtin_convertvector(v, bf16x2_t); return __builtin_bit_cast(unsigned, b); }
; __device__ __forceinline__ void phase_norm(const Params& P, int l, int which, bool first) {
;     ...
;     for (int r = gw; r < ROWS; r += NGW) {
;         const int b = r / TT, t = r - b * TT; const int bb = (t < CTX) ? 16 : b;
;         float* xr = xrow_ptr(P, r);
;         const float* src = first ? ((t < CTX) ? P.ctx + ((size_t)b * CTX + t) * DM : P.x + ((size_t)b * SEQ + (t - CTX)) * DM) : xr;
;         f32x4 v[4]; float s2 = 0.f;
; #pragma unroll
;         for (int j = 0; j < 4; ++j) { v[j] = *((const f32x4*)src + lane + 64 * j); s2 += (v[j].x * v[j].x + v[j].y * v[j].y) + (v[j].z * v[j].z + v[j].w * v[j].w); }
;         if (first) {
; #pragma unroll
;             for (int j = 0; j < 4; ++j) *((f32x4*)xr + lane + 64 * j) = v[j];
;         }
;         const float rstd = 1.0f / sqrtf(wave_sum(s2, lane) * (1.0f / DM) + RMS_EPS);
;         const float* mrow = mod + (size_t)bb * MODW;
; #pragma unroll
;         for (int j = 0; j < 4; ++j) {
;             const int c0 = 4 * (lane + 64 * j);
;             const f32x4 g = *(const f32x4*)(gain + c0), sh = *(const f32x4*)(mrow + c0), scl = *(const f32x4*)(mrow + DM + c0);
;             const f32x4 y = v[j] * rstd * g * (scl + 1.0f) + sh;
;             u32x2 w; w.x = pk2(y.x, y.y); w.y = pk2(y.z, y.w);
;             *(u32x2*)(H + (size_t)r * DM + c0) = w;
;         }
;     }
	v_add_f32_e32 v34, v34, v32
	ds_bpermute_b32 v32, v123, v34
	s_waitcnt lgkmcnt(0)
	v_add_f32_e32 v34, v34, v32
	ds_bpermute_b32 v32, v124, v34
	s_waitcnt lgkmcnt(0)
	v_add_f32_e32 v34, v34, v32
	ds_bpermute_b32 v32, v125, v34
	s_waitcnt lgkmcnt(0)
	v_add_f32_e32 v34, v34, v32
	ds_bpermute_b32 v32, v126, v34
	s_waitcnt lgkmcnt(0)
	v_add_f32_e32 v34, v34, v32
	ds_bpermute_b32 v32, v127, v34
	s_waitcnt lgkmcnt(0)
	v_add_f32_e32 v34, v34, v32
	v_fmamk_f32 v34, v34, 0x3a800000, v201
	v_cmp_gt_f32_e32 vcc, 0xf800000, v34
	v_mul_f32_e32 v32, 0x4f800000, v34
	s_nop 0
	v_cndmask_b32_e32 v34, v34, v32, vcc
	v_sqrt_f32_e32 v32, v34
	s_nop 0
	v_add_u32_e32 v35, -1, v32
	v_fma_f32 v36, -v35, v32, v34
	v_cmp_ge_f32_e64 s[38:39], 0, v36
	v_add_u32_e32 v36, 1, v32
	s_nop 0
	v_cndmask_b32_e64 v35, v32, v35, s[38:39]
	v_fma_f32 v32, -v36, v32, v34
	v_cmp_lt_f32_e64 s[38:39], 0, v32
	s_nop 1
	v_cndmask_b32_e64 v32, v35, v36, s[38:39]
	v_mul_f32_e32 v35, 0x37800000, v32
	v_cndmask_b32_e32 v32, v32, v35, vcc
	v_cmp_class_f32_e32 vcc, v34, v202
	s_nop 1
	v_cndmask_b32_e32 v34, v32, v34, vcc
	v_div_scale_f32 v32, s[38:39], v34, v34, 1.0
	v_rcp_f32_e32 v35, v32
	s_nop 0
	v_fma_f32 v36, -v32, v35, 1.0
	v_fmac_f32_e32 v35, v36, v35
	v_div_scale_f32 v36, vcc, 1.0, v34, 1.0
	v_mul_f32_e32 v37, v36, v35
	v_fma_f32 v178, -v32, v37, v36
	v_fmac_f32_e32 v37, v178, v35
	v_fma_f32 v32, -v32, v37, v36
	v_div_fmas_f32 v32, v32, v35, v37
	v_div_fixup_f32 v179, v32, v34, 1.0
	s_lshl_b32 s8, s101, 11
	s_add_u32 s12, s58, s8
	s_addc_u32 s13, s59, 0
	s_add_u32 s12, s12, 0x5500000
	s_addc_u32 s13, s13, 0
	s_waitcnt vmcnt(8)
	v_mul_f32_e32 v193, v0, v179
	v_add_f32_e32 v192, 1.0, v72
	v_mul_f32_e32 v193, v162, v193
	v_fma_f32 v180, v192, v193, v56
	v_mul_f32_e32 v193, v1, v179
	v_add_f32_e32 v192, 1.0, v73
	v_mul_f32_e32 v193, v163, v193
	v_fma_f32 v181, v192, v193, v57
	v_mul_f32_e32 v193, v2, v179
	v_add_f32_e32 v192, 1.0, v74
	v_mul_f32_e32 v193, v164, v193
	v_fma_f32 v182, v192, v193, v58
	v_mul_f32_e32 v193, v3, v179
	v_add_f32_e32 v192, 1.0, v75
	v_mul_f32_e32 v193, v165, v193
	v_fma_f32 v183, v192, v193, v59
	v_cvt_pk_bf16_f32 v184, v180, v181
	v_cvt_pk_bf16_f32 v185, v182, v183
	global_store_dwordx2 v121, v[184:185], s[12:13]
	v_mul_f32_e32 v193, v4, v179
	v_add_f32_e32 v192, 1.0, v76
	v_mul_f32_e32 v193, v166, v193
	v_fma_f32 v180, v192, v193, v60
	v_mul_f32_e32 v193, v5, v179
	v_add_f32_e32 v192, 1.0, v77
	v_mul_f32_e32 v193, v167, v193
	v_fma_f32 v181, v192, v193, v61
	v_mul_f32_e32 v193, v6, v179
	v_add_f32_e32 v192, 1.0, v78
	v_mul_f32_e32 v193, v168, v193
	v_fma_f32 v182, v192, v193, v62
	v_mul_f32_e32 v193, v7, v179
	v_add_f32_e32 v192, 1.0, v79
	v_mul_f32_e32 v193, v169, v193
	v_fma_f32 v183, v192, v193, v63
	v_cvt_pk_bf16_f32 v186, v180, v181
	v_cvt_pk_bf16_f32 v187, v182, v183
	global_store_dwordx2 v121, v[186:187], s[12:13] offset:512
	v_mul_f32_e32 v193, v8, v179
	v_add_f32_e32 v192, 1.0, v80
	v_mul_f32_e32 v193, v170, v193
	v_fma_f32 v180, v192, v193, v64
	v_mul_f32_e32 v193, v9, v179
	v_add_f32_e32 v192, 1.0, v81
	v_mul_f32_e32 v193, v171, v193
	v_fma_f32 v181, v192, v193, v65
	v_mul_f32_e32 v193, v10, v179
	v_add_f32_e32 v192, 1.0, v82
	v_mul_f32_e32 v193, v172, v193
	v_fma_f32 v182, v192, v193, v66
	v_mul_f32_e32 v193, v11, v179
	v_add_f32_e32 v192, 1.0, v83
	v_mul_f32_e32 v193, v173, v193
	v_fma_f32 v183, v192, v193, v67
	v_cvt_pk_bf16_f32 v188, v180, v181
	v_cvt_pk_bf16_f32 v189, v182, v183
	global_store_dwordx2 v121, v[188:189], s[12:13] offset:1024
	v_mul_f32_e32 v193, v12, v179
	v_add_f32_e32 v192, 1.0, v84
	v_mul_f32_e32 v193, v174, v193
	v_fma_f32 v180, v192, v193, v68
	v_mul_f32_e32 v193, v13, v179
	v_add_f32_e32 v192, 1.0, v85
	v_mul_f32_e32 v193, v175, v193
	v_fma_f32 v181, v192, v193, v69
	v_mul_f32_e32 v193, v14, v179
	v_add_f32_e32 v192, 1.0, v86
	v_mul_f32_e32 v193, v176, v193
	v_fma_f32 v182, v192, v193, v70
	v_mul_f32_e32 v193, v15, v179
	v_add_f32_e32 v192, 1.0, v87
	v_mul_f32_e32 v193, v177, v193
	v_fma_f32 v183, v192, v193, v71
	v_cvt_pk_bf16_f32 v190, v180, v181
	v_cvt_pk_bf16_f32 v191, v182, v183
	global_store_dwordx2 v121, v[190:191], s[12:13] offset:1536
	s_mul_i32 s100, s68, 3
	s_add_u32 s100, s100, s101
	s_cmp_le_u32 s100, s71
	s_cselect_b32 s100, s100, s101
	s_lshr_b32 s8, s100, 8
	s_mul_i32 s8, s8, 57
	s_lshr_b32 s8, s8, 9
	s_mul_i32 s9, s8, 0x900
	s_sub_u32 s9, s100, s9
	s_lshl_b32 s12, s8, 11
	s_add_u32 s12, s12, s9
	s_sub_u32 s12, s12, 0x100
	s_lshl_b32 s8, s8, 8
	s_add_u32 s8, s8, s9
	s_cmp_lt_u32 s9, 0x100
	s_cselect_b32 s8, s8, s12
	s_cselect_b32 s12, s36, s56
	s_cselect_b32 s13, s37, s57
	s_lshl_b32 s8, s8, 12
	s_add_u32 s12, s12, s8
	s_addc_u32 s13, s13, 0
	global_load_dwordx4 v[0:3], v120, s[12:13]
	global_load_dwordx4 v[4:7], v120, s[12:13] offset:1024
	global_load_dwordx4 v[8:11], v120, s[12:13] offset:2048
	global_load_dwordx4 v[12:15], v120, s[12:13] offset:3072
	s_add_u32 s101, s101, s68
	s_cmp_gt_u32 s101, s71
	s_cbranch_scc1 .Lnf_n1_exit
; __device__ __forceinline__ unsigned pk2(float lo, float hi) { f32x2_t v = {lo, hi}; bf16x2_t b = __builtin_convertvector(v, bf16x2_t); return __builtin_bit_cast(unsigned, b); }
; __device__ __forceinline__ void phase_norm(const Params& P, int l, int which, bool first) {
;     ...
;     for (int r = gw; r < ROWS; r += NGW) {
;         const int b = r / TT, t = r - b * TT; const int bb = (t < CTX) ? 16 : b;
;         float* xr = xrow_ptr(P, r);
;         const float* src = first ? ((t < CTX) ? P.ctx + ((size_t)b * CTX + t) * DM : P.x + ((size_t)b * SEQ + (t - CTX)) * DM) : xr;
;         f32x4 v[4]; float s2 = 0.f;
; #pragma unroll
;         for (int j = 0; j < 4; ++j) { v[j] = *((const f32x4*)src + lane + 64 * j); s2 += (v[j].x * v[j].x + v[j].y * v[j].y) + (v[j].z * v[j].z + v[j].w * v[j].w); }
;         if (first) {
; #pragma unroll
;             for (int j = 0; j < 4; ++j) *((f32x4*)xr + lane + 64 * j) = v[j];
;         }
;         const float rstd = 1.0f / sqrtf(wave_sum(s2, lane) * (1.0f / DM) + RMS_EPS);
;         const float* mrow = mod + (size_t)bb * MODW;
; #pragma unroll
;         for (int j = 0; j < 4; ++j) {
;             const int c0 = 4 * (lane + 64 * j);
;             const f32x4 g = *(const f32x4*)(gain + c0), sh = *(const f32x4*)(mrow + c0), scl = *(const f32x4*)(mrow + DM + c0);
;             const f32x4 y = v[j] * rstd * g * (scl + 1.0f) + sh;
;             u32x2 w; w.x = pk2(y.x, y.y); w.y = pk2(y.z, y.w);
;             *(u32x2*)(H + (size_t)r * DM + c0) = w;
;         }
;     }
	s_waitcnt vmcnt(28)
	s_add_u32 s100, s101, s68
	s_cmp_le_u32 s100, s71
	s_cselect_b32 s100, s100, s101
	s_lshr_b32 s8, s100, 8
	s_mul_i32 s8, s8, 57
	s_lshr_b32 s8, s8, 9
	s_mul_i32 s9, s8, 0x900
	s_sub_u32 s9, s100, s9
	s_cmp_lt_u32 s9, 0x100
	s_cselect_b32 s8, 16, s8
	s_mul_i32 s8, s8, 0x6000
	s_add_u32 s12, s50, s8
	s_addc_u32 s13, s51, 0
	global_load_dwordx4 v[130:133], v120, s[12:13] offset:-4096
	global_load_dwordx4 v[134:137], v120, s[12:13] offset:-3072
	global_load_dwordx4 v[138:141], v120, s[12:13] offset:-2048
	global_load_dwordx4 v[142:145], v120, s[12:13] offset:-1024
	global_load_dwordx4 v[146:149], v120, s[12:13]
	global_load_dwordx4 v[150:153], v120, s[12:13] offset:1024
	global_load_dwordx4 v[154:157], v120, s[12:13] offset:2048
	global_load_dwordx4 v[158:161], v120, s[12:13] offset:3072
	v_mul_f32_e32 v32, v17, v17
	v_mul_f32_e32 v33, v19, v19
	v_fmac_f32_e32 v32, v16, v16
	v_fmac_f32_e32 v33, v18, v18
	v_add_f32_e32 v34, v32, v33
	v_mul_f32_e32 v32, v21, v21
	v_mul_f32_e32 v33, v23, v23
	v_fmac_f32_e32 v32, v20, v20
	v_fmac_f32_e32 v33, v22, v22
	v_add_f32_e32 v32, v32, v33
	v_add_f32_e32 v34, v34, v32
	v_mul_f32_e32 v32, v25, v25
	v_mul_f32_e32 v33, v27, v27
	v_fmac_f32_e32 v32, v24, v24
	v_fmac_f32_e32 v33, v26, v26
	v_add_f32_e32 v32, v32, v33
	v_add_f32_e32 v34, v34, v32
	v_mul_f32_e32 v32, v29, v29
	v_mul_f32_e32 v33, v31, v31
	v_fmac_f32_e32 v32, v28, v28
	v_fmac_f32_e32 v33, v30, v30
	v_add_f32_e32 v32, v32, v33
	v_add_f32_e32 v34, v34, v32
	ds_bpermute_b32 v32, v122, v34
	s_waitcnt lgkmcnt(0)
	v_add_f32_e32 v34, v34, v32
	ds_bpermute_b32 v32, v123, v34
	s_waitcnt lgkmcnt(0)
	v_add_f32_e32 v34, v34, v32
	ds_bpermute_b32 v32, v124, v34
	s_waitcnt lgkmcnt(0)
	v_add_f32_e32 v34, v34, v32
	ds_bpermute_b32 v32, v125, v34
	s_waitcnt lgkmcnt(0)
	v_add_f32_e32 v34, v34, v32
	ds_bpermute_b32 v32, v126, v34
	s_waitcnt lgkmcnt(0)
	v_add_f32_e32 v34, v34, v32
	ds_bpermute_b32 v32, v127, v34
	s_waitcnt lgkmcnt(0)
	v_add_f32_e32 v34, v34, v32
	v_fmamk_f32 v34, v34, 0x3a800000, v201
	v_cmp_gt_f32_e32 vcc, 0xf800000, v34
	v_mul_f32_e32 v32, 0x4f800000, v34
	s_nop 0
	v_cndmask_b32_e32 v34, v34, v32, vcc
	v_sqrt_f32_e32 v32, v34
	s_nop 0
	v_add_u32_e32 v35, -1, v32
	v_fma_f32 v36, -v35, v32, v34
	v_cmp_ge_f32_e64 s[38:39], 0, v36
	v_add_u32_e32 v36, 1, v32
	s_nop 0
	v_cndmask_b32_e64 v35, v32, v35, s[38:39]
	v_fma_f32 v32, -v36, v32, v34
	v_cmp_lt_f32_e64 s[38:39], 0, v32
	s_nop 1
	v_cndmask_b32_e64 v32, v35, v36, s[38:39]
	v_mul_f32_e32 v35, 0x37800000, v32
	v_cndmask_b32_e32 v32, v32, v35, vcc
	v_cmp_class_f32_e32 vcc, v34, v202
	s_nop 1
	v_cndmask_b32_e32 v34, v32, v34, vcc
	v_div_scale_f32 v32, s[38:39], v34, v34, 1.0
	v_rcp_f32_e32 v35, v32
	s_nop 0
	v_fma_f32 v36, -v32, v35, 1.0
	v_fmac_f32_e32 v35, v36, v35
	v_div_scale_f32 v36, vcc, 1.0, v34, 1.0
	v_mul_f32_e32 v37, v36, v35
	v_fma_f32 v178, -v32, v37, v36
	v_fmac_f32_e32 v37, v178, v35
	v_fma_f32 v32, -v32, v37, v36
	v_div_fmas_f32 v32, v32, v35, v37
	v_div_fixup_f32 v179, v32, v34, 1.0
	s_lshl_b32 s8, s101, 11
	s_add_u32 s12, s58, s8
	s_addc_u32 s13, s59, 0
	s_add_u32 s12, s12, 0x5500000
	s_addc_u32 s13, s13, 0
	s_waitcnt vmcnt(16)
	v_mul_f32_e32 v193, v16, v179
	v_add_f32_e32 v192, 1.0, v104
	v_mul_f32_e32 v193, v162, v193
	v_fma_f32 v180, v192, v193, v88
	v_mul_f32_e32 v193, v17, v179
	v_add_f32_e32 v192, 1.0, v105
	v_mul_f32_e32 v193, v163, v193
	v_fma_f32 v181, v192, v193, v89
	v_mul_f32_e32 v193, v18, v179
	v_add_f32_e32 v192, 1.0, v106
	v_mul_f32_e32 v193, v164, v193
	v_fma_f32 v182, v192, v193, v90
	v_mul_f32_e32 v193, v19, v179
	v_add_f32_e32 v192, 1.0, v107
	v_mul_f32_e32 v193, v165, v193
	v_fma_f32 v183, v192, v193, v91
	v_cvt_pk_bf16_f32 v184, v180, v181
	v_cvt_pk_bf16_f32 v185, v182, v183
	global_store_dwordx2 v121, v[184:185], s[12:13]
	v_mul_f32_e32 v193, v20, v179
	v_add_f32_e32 v192, 1.0, v108
	v_mul_f32_e32 v193, v166, v193
	v_fma_f32 v180, v192, v193, v92
	v_mul_f32_e32 v193, v21, v179
	v_add_f32_e32 v192, 1.0, v109
	v_mul_f32_e32 v193, v167, v193
	v_fma_f32 v181, v192, v193, v93
	v_mul_f32_e32 v193, v22, v179
	v_add_f32_e32 v192, 1.0, v110
	v_mul_f32_e32 v193, v168, v193
	v_fma_f32 v182, v192, v193, v94
	v_mul_f32_e32 v193, v23, v179
	v_add_f32_e32 v192, 1.0, v111
	v_mul_f32_e32 v193, v169, v193
	v_fma_f32 v183, v192, v193, v95
	v_cvt_pk_bf16_f32 v186, v180, v181
	v_cvt_pk_bf16_f32 v187, v182, v183
	global_store_dwordx2 v121, v[186:187], s[12:13] offset:512
	v_mul_f32_e32 v193, v24, v179
	v_add_f32_e32 v192, 1.0, v112
	v_mul_f32_e32 v193, v170, v193
	v_fma_f32 v180, v192, v193, v96
	v_mul_f32_e32 v193, v25, v179
	v_add_f32_e32 v192, 1.0, v113
	v_mul_f32_e32 v193, v171, v193
	v_fma_f32 v181, v192, v193, v97
	v_mul_f32_e32 v193, v26, v179
	v_add_f32_e32 v192, 1.0, v114
	v_mul_f32_e32 v193, v172, v193
	v_fma_f32 v182, v192, v193, v98
	v_mul_f32_e32 v193, v27, v179
	v_add_f32_e32 v192, 1.0, v115
	v_mul_f32_e32 v193, v173, v193
	v_fma_f32 v183, v192, v193, v99
	v_cvt_pk_bf16_f32 v188, v180, v181
	v_cvt_pk_bf16_f32 v189, v182, v183
	global_store_dwordx2 v121, v[188:189], s[12:13] offset:1024
	v_mul_f32_e32 v193, v28, v179
	v_add_f32_e32 v192, 1.0, v116
	v_mul_f32_e32 v193, v174, v193
	v_fma_f32 v180, v192, v193, v100
	v_mul_f32_e32 v193, v29, v179
	v_add_f32_e32 v192, 1.0, v117
	v_mul_f32_e32 v193, v175, v193
	v_fma_f32 v181, v192, v193, v101
	v_mul_f32_e32 v193, v30, v179
	v_add_f32_e32 v192, 1.0, v118
	v_mul_f32_e32 v193, v176, v193
	v_fma_f32 v182, v192, v193, v102
	v_mul_f32_e32 v193, v31, v179
	v_add_f32_e32 v192, 1.0, v119
	v_mul_f32_e32 v193, v177, v193
	v_fma_f32 v183, v192, v193, v103
	v_cvt_pk_bf16_f32 v190, v180, v181
	v_cvt_pk_bf16_f32 v191, v182, v183
	global_store_dwordx2 v121, v[190:191], s[12:13] offset:1536
	s_mul_i32 s100, s68, 3
	s_add_u32 s100, s100, s101
	s_cmp_le_u32 s100, s71
	s_cselect_b32 s100, s100, s101
	s_lshr_b32 s8, s100, 8
	s_mul_i32 s8, s8, 57
	s_lshr_b32 s8, s8, 9
	s_mul_i32 s9, s8, 0x900
	s_sub_u32 s9, s100, s9
	s_lshl_b32 s12, s8, 11
	s_add_u32 s12, s12, s9
	s_sub_u32 s12, s12, 0x100
	s_lshl_b32 s8, s8, 8
	s_add_u32 s8, s8, s9
	s_cmp_lt_u32 s9, 0x100
	s_cselect_b32 s8, s8, s12
	s_cselect_b32 s12, s36, s56
	s_cselect_b32 s13, s37, s57
	s_lshl_b32 s8, s8, 12
	s_add_u32 s12, s12, s8
	s_addc_u32 s13, s13, 0
	global_load_dwordx4 v[16:19], v120, s[12:13]
	global_load_dwordx4 v[20:23], v120, s[12:13] offset:1024
	global_load_dwordx4 v[24:27], v120, s[12:13] offset:2048
	global_load_dwordx4 v[28:31], v120, s[12:13] offset:3072
	s_add_u32 s101, s101, s68
	s_cmp_gt_u32 s101, s71
	s_cbranch_scc1 .Lnf_n1_exit
; __device__ __forceinline__ unsigned pk2(float lo, float hi) { f32x2_t v = {lo, hi}; bf16x2_t b = __builtin_convertvector(v, bf16x2_t); return __builtin_bit_cast(unsigned, b); }
; __device__ __forceinline__ void phase_norm(const Params& P, int l, int which, bool first) {
;     ...
;     for (int r = gw; r < ROWS; r += NGW) {
;         const int b = r / TT, t = r - b * TT; const int bb = (t < CTX) ? 16 : b;
;         float* xr = xrow_ptr(P, r);
;         const float* src = first ? ((t < CTX) ? P.ctx + ((size_t)b * CTX + t) * DM : P.x + ((size_t)b * SEQ + (t - CTX)) * DM) : xr;
;         f32x4 v[4]; float s2 = 0.f;
; #pragma unroll
;         for (int j = 0; j < 4; ++j) { v[j] = *((const f32x4*)src + lane + 64 * j); s2 += (v[j].x * v[j].x + v[j].y * v[j].y) + (v[j].z * v[j].z + v[j].w * v[j].w); }
;         if (first) {
; #pragma unroll
;             for (int j = 0; j < 4; ++j) *((f32x4*)xr + lane + 64 * j) = v[j];
;         }
;         const float rstd = 1.0f / sqrtf(wave_sum(s2, lane) * (1.0f / DM) + RMS_EPS);
;         const float* mrow = mod + (size_t)bb * MODW;
; #pragma unroll
;         for (int j = 0; j < 4; ++j) {
;             const int c0 = 4 * (lane + 64 * j);
;             const f32x4 g = *(const f32x4*)(gain + c0), sh = *(const f32x4*)(mrow + c0), scl = *(const f32x4*)(mrow + DM + c0);
;             const f32x4 y = v[j] * rstd * g * (scl + 1.0f) + sh;
;             u32x2 w; w.x = pk2(y.x, y.y); w.y = pk2(y.z, y.w);
;             *(u32x2*)(H + (size_t)r * DM + c0) = w;
;         }
;     }
	s_waitcnt vmcnt(32)
	s_add_u32 s100, s101, s68
	s_cmp_le_u32 s100, s71
	s_cselect_b32 s100, s100, s101
	s_lshr_b32 s8, s100, 8
	s_mul_i32 s8, s8, 57
	s_lshr_b32 s8, s8, 9
	s_mul_i32 s9, s8, 0x900
	s_sub_u32 s9, s100, s9
	s_cmp_lt_u32 s9, 0x100
	s_cselect_b32 s8, 16, s8
	s_mul_i32 s8, s8, 0x6000
	s_add_u32 s12, s50, s8
	s_addc_u32 s13, s51, 0
	global_load_dwordx4 v[56:59], v120, s[12:13] offset:-4096
	global_load_dwordx4 v[60:63], v120, s[12:13] offset:-3072
	global_load_dwordx4 v[64:67], v120, s[12:13] offset:-2048
	global_load_dwordx4 v[68:71], v120, s[12:13] offset:-1024
	global_load_dwordx4 v[72:75], v120, s[12:13]
	global_load_dwordx4 v[76:79], v120, s[12:13] offset:1024
	global_load_dwordx4 v[80:83], v120, s[12:13] offset:2048
	global_load_dwordx4 v[84:87], v120, s[12:13] offset:3072
	v_mul_f32_e32 v32, v41, v41
	v_mul_f32_e32 v33, v43, v43
	v_fmac_f32_e32 v32, v40, v40
	v_fmac_f32_e32 v33, v42, v42
	v_add_f32_e32 v34, v32, v33
	v_mul_f32_e32 v32, v45, v45
	v_mul_f32_e32 v33, v47, v47
	v_fmac_f32_e32 v32, v44, v44
	v_fmac_f32_e32 v33, v46, v46
	v_add_f32_e32 v32, v32, v33
	v_add_f32_e32 v34, v34, v32
	v_mul_f32_e32 v32, v49, v49
	v_mul_f32_e32 v33, v51, v51
	v_fmac_f32_e32 v32, v48, v48
	v_fmac_f32_e32 v33, v50, v50
	v_add_f32_e32 v32, v32, v33
	v_add_f32_e32 v34, v34, v32
	v_mul_f32_e32 v32, v53, v53
	v_mul_f32_e32 v33, v55, v55
	v_fmac_f32_e32 v32, v52, v52
	v_fmac_f32_e32 v33, v54, v54
	v_add_f32_e32 v32, v32, v33
	v_add_f32_e32 v34, v34, v32
	ds_bpermute_b32 v32, v122, v34
	s_waitcnt lgkmcnt(0)
	v_add_f32_e32 v34, v34, v32
	ds_bpermute_b32 v32, v123, v34
	s_waitcnt lgkmcnt(0)
	v_add_f32_e32 v34, v34, v32
	ds_bpermute_b32 v32, v124, v34
	s_waitcnt lgkmcnt(0)
	v_add_f32_e32 v34, v34, v32
	ds_bpermute_b32 v32, v125, v34
	s_waitcnt lgkmcnt(0)
	v_add_f32_e32 v34, v34, v32
	ds_bpermute_b32 v32, v126, v34
	s_waitcnt lgkmcnt(0)
	v_add_f32_e32 v34, v34, v32
	ds_bpermute_b32 v32, v127, v34
	s_waitcnt lgkmcnt(0)
	v_add_f32_e32 v34, v34, v32
	v_fmamk_f32 v34, v34, 0x3a800000, v201
	v_cmp_gt_f32_e32 vcc, 0xf800000, v34
	v_mul_f32_e32 v32, 0x4f800000, v34
	s_nop 0
	v_cndmask_b32_e32 v34, v34, v32, vcc
	v_sqrt_f32_e32 v32, v34
	s_nop 0
	v_add_u32_e32 v35, -1, v32
	v_fma_f32 v36, -v35, v32, v34
	v_cmp_ge_f32_e64 s[38:39], 0, v36
	v_add_u32_e32 v36, 1, v32
	s_nop 0
	v_cndmask_b32_e64 v35, v32, v35, s[38:39]
	v_fma_f32 v32, -v36, v32, v34
	v_cmp_lt_f32_e64 s[38:39], 0, v32
	s_nop 1
	v_cndmask_b32_e64 v32, v35, v36, s[38:39]
	v_mul_f32_e32 v35, 0x37800000, v32
	v_cndmask_b32_e32 v32, v32, v35, vcc
	v_cmp_class_f32_e32 vcc, v34, v202
	s_nop 1
	v_cndmask_b32_e32 v34, v32, v34, vcc
	v_div_scale_f32 v32, s[38:39], v34, v34, 1.0
	v_rcp_f32_e32 v35, v32
	s_nop 0
	v_fma_f32 v36, -v32, v35, 1.0
	v_fmac_f32_e32 v35, v36, v35
	v_div_scale_f32 v36, vcc, 1.0, v34, 1.0
	v_mul_f32_e32 v37, v36, v35
	v_fma_f32 v178, -v32, v37, v36
	v_fmac_f32_e32 v37, v178, v35
	v_fma_f32 v32, -v32, v37, v36
	v_div_fmas_f32 v32, v32, v35, v37
	v_div_fixup_f32 v179, v32, v34, 1.0
	s_lshl_b32 s8, s101, 11
	s_add_u32 s12, s58, s8
	s_addc_u32 s13, s59, 0
	s_add_u32 s12, s12, 0x5500000
	s_addc_u32 s13, s13, 0
	s_waitcnt vmcnt(16)
	v_mul_f32_e32 v193, v40, v179
	v_add_f32_e32 v192, 1.0, v146
	v_mul_f32_e32 v193, v162, v193
	v_fma_f32 v180, v192, v193, v130
	v_mul_f32_e32 v193, v41, v179
	v_add_f32_e32 v192, 1.0, v147
	v_mul_f32_e32 v193, v163, v193
	v_fma_f32 v181, v192, v193, v131
	v_mul_f32_e32 v193, v42, v179
	v_add_f32_e32 v192, 1.0, v148
	v_mul_f32_e32 v193, v164, v193
	v_fma_f32 v182, v192, v193, v132
	v_mul_f32_e32 v193, v43, v179
	v_add_f32_e32 v192, 1.0, v149
	v_mul_f32_e32 v193, v165, v193
	v_fma_f32 v183, v192, v193, v133
	v_cvt_pk_bf16_f32 v184, v180, v181
	v_cvt_pk_bf16_f32 v185, v182, v183
	global_store_dwordx2 v121, v[184:185], s[12:13]
	v_mul_f32_e32 v193, v44, v179
	v_add_f32_e32 v192, 1.0, v150
	v_mul_f32_e32 v193, v166, v193
	v_fma_f32 v180, v192, v193, v134
	v_mul_f32_e32 v193, v45, v179
	v_add_f32_e32 v192, 1.0, v151
	v_mul_f32_e32 v193, v167, v193
	v_fma_f32 v181, v192, v193, v135
	v_mul_f32_e32 v193, v46, v179
	v_add_f32_e32 v192, 1.0, v152
	v_mul_f32_e32 v193, v168, v193
	v_fma_f32 v182, v192, v193, v136
	v_mul_f32_e32 v193, v47, v179
	v_add_f32_e32 v192, 1.0, v153
	v_mul_f32_e32 v193, v169, v193
	v_fma_f32 v183, v192, v193, v137
	v_cvt_pk_bf16_f32 v186, v180, v181
	v_cvt_pk_bf16_f32 v187, v182, v183
	global_store_dwordx2 v121, v[186:187], s[12:13] offset:512
	v_mul_f32_e32 v193, v48, v179
	v_add_f32_e32 v192, 1.0, v154
	v_mul_f32_e32 v193, v170, v193
	v_fma_f32 v180, v192, v193, v138
	v_mul_f32_e32 v193, v49, v179
	v_add_f32_e32 v192, 1.0, v155
	v_mul_f32_e32 v193, v171, v193
	v_fma_f32 v181, v192, v193, v139
	v_mul_f32_e32 v193, v50, v179
	v_add_f32_e32 v192, 1.0, v156
	v_mul_f32_e32 v193, v172, v193
	v_fma_f32 v182, v192, v193, v140
	v_mul_f32_e32 v193, v51, v179
	v_add_f32_e32 v192, 1.0, v157
	v_mul_f32_e32 v193, v173, v193
	v_fma_f32 v183, v192, v193, v141
	v_cvt_pk_bf16_f32 v188, v180, v181
	v_cvt_pk_bf16_f32 v189, v182, v183
	global_store_dwordx2 v121, v[188:189], s[12:13] offset:1024
	v_mul_f32_e32 v193, v52, v179
	v_add_f32_e32 v192, 1.0, v158
	v_mul_f32_e32 v193, v174, v193
	v_fma_f32 v180, v192, v193, v142
	v_mul_f32_e32 v193, v53, v179
	v_add_f32_e32 v192, 1.0, v159
	v_mul_f32_e32 v193, v175, v193
	v_fma_f32 v181, v192, v193, v143
	v_mul_f32_e32 v193, v54, v179
	v_add_f32_e32 v192, 1.0, v160
	v_mul_f32_e32 v193, v176, v193
	v_fma_f32 v182, v192, v193, v144
	v_mul_f32_e32 v193, v55, v179
	v_add_f32_e32 v192, 1.0, v161
	v_mul_f32_e32 v193, v177, v193
	v_fma_f32 v183, v192, v193, v145
	v_cvt_pk_bf16_f32 v190, v180, v181
	v_cvt_pk_bf16_f32 v191, v182, v183
	global_store_dwordx2 v121, v[190:191], s[12:13] offset:1536
	s_mul_i32 s100, s68, 3
	s_add_u32 s100, s100, s101
	s_cmp_le_u32 s100, s71
	s_cselect_b32 s100, s100, s101
	s_lshr_b32 s8, s100, 8
	s_mul_i32 s8, s8, 57
	s_lshr_b32 s8, s8, 9
	s_mul_i32 s9, s8, 0x900
	s_sub_u32 s9, s100, s9
	s_lshl_b32 s12, s8, 11
	s_add_u32 s12, s12, s9
	s_sub_u32 s12, s12, 0x100
	s_lshl_b32 s8, s8, 8
	s_add_u32 s8, s8, s9
	s_cmp_lt_u32 s9, 0x100
	s_cselect_b32 s8, s8, s12
	s_cselect_b32 s12, s36, s56
	s_cselect_b32 s13, s37, s57
	s_lshl_b32 s8, s8, 12
	s_add_u32 s12, s12, s8
	s_addc_u32 s13, s13, 0
	global_load_dwordx4 v[40:43], v120, s[12:13]
	global_load_dwordx4 v[44:47], v120, s[12:13] offset:1024
	global_load_dwordx4 v[48:51], v120, s[12:13] offset:2048
	global_load_dwordx4 v[52:55], v120, s[12:13] offset:3072
	s_add_u32 s101, s101, s68
	s_cmp_gt_u32 s101, s71
	s_cbranch_scc1 .Lnf_n1_exit
; __device__ __forceinline__ unsigned pk2(float lo, float hi) { f32x2_t v = {lo, hi}; bf16x2_t b = __builtin_convertvector(v, bf16x2_t); return __builtin_bit_cast(unsigned, b); }
; __device__ __forceinline__ void phase_norm(const Params& P, int l, int which, bool first) {
;     ...
;     for (int r = gw; r < ROWS; r += NGW) {
;         const int b = r / TT, t = r - b * TT; const int bb = (t < CTX) ? 16 : b;
;         float* xr = xrow_ptr(P, r);
;         const float* src = first ? ((t < CTX) ? P.ctx + ((size_t)b * CTX + t) * DM : P.x + ((size_t)b * SEQ + (t - CTX)) * DM) : xr;
;         f32x4 v[4]; float s2 = 0.f;
; #pragma unroll
;         for (int j = 0; j < 4; ++j) { v[j] = *((const f32x4*)src + lane + 64 * j); s2 += (v[j].x * v[j].x + v[j].y * v[j].y) + (v[j].z * v[j].z + v[j].w * v[j].w); }
;         if (first) {
; #pragma unroll
;             for (int j = 0; j < 4; ++j) *((f32x4*)xr + lane + 64 * j) = v[j];
;         }
;         const float rstd = 1.0f / sqrtf(wave_sum(s2, lane) * (1.0f / DM) + RMS_EPS);
;         const float* mrow = mod + (size_t)bb * MODW;
; #pragma unroll
;         for (int j = 0; j < 4; ++j) {
;             const int c0 = 4 * (lane + 64 * j);
;             const f32x4 g = *(const f32x4*)(gain + c0), sh = *(const f32x4*)(mrow + c0), scl = *(const f32x4*)(mrow + DM + c0);
;             const f32x4 y = v[j] * rstd * g * (scl + 1.0f) + sh;
;             u32x2 w; w.x = pk2(y.x, y.y); w.y = pk2(y.z, y.w);
;             *(u32x2*)(H + (size_t)r * DM + c0) = w;
;         }
;     }
.Lnf_n1_loop:
	s_waitcnt vmcnt(32)
	s_add_u32 s100, s101, s68
	s_cmp_le_u32 s100, s71
	s_cselect_b32 s100, s100, s101
	s_lshr_b32 s8, s100, 8
	s_mul_i32 s8, s8, 57
	s_lshr_b32 s8, s8, 9
	s_mul_i32 s9, s8, 0x900
	s_sub_u32 s9, s100, s9
	s_cmp_lt_u32 s9, 0x100
	s_cselect_b32 s8, 16, s8
	s_mul_i32 s8, s8, 0x6000
	s_add_u32 s12, s50, s8
	s_addc_u32 s13, s51, 0
	global_load_dwordx4 v[88:91], v120, s[12:13] offset:-4096
	global_load_dwordx4 v[92:95], v120, s[12:13] offset:-3072
	global_load_dwordx4 v[96:99], v120, s[12:13] offset:-2048
	global_load_dwordx4 v[100:103], v120, s[12:13] offset:-1024
	global_load_dwordx4 v[104:107], v120, s[12:13]
	global_load_dwordx4 v[108:111], v120, s[12:13] offset:1024
	global_load_dwordx4 v[112:115], v120, s[12:13] offset:2048
	global_load_dwordx4 v[116:119], v120, s[12:13] offset:3072
	v_mul_f32_e32 v32, v1, v1
	v_mul_f32_e32 v33, v3, v3
	v_fmac_f32_e32 v32, v0, v0
	v_fmac_f32_e32 v33, v2, v2
	v_add_f32_e32 v34, v32, v33
	v_mul_f32_e32 v32, v5, v5
	v_mul_f32_e32 v33, v7, v7
	v_fmac_f32_e32 v32, v4, v4
	v_fmac_f32_e32 v33, v6, v6
	v_add_f32_e32 v32, v32, v33
	v_add_f32_e32 v34, v34, v32
	v_mul_f32_e32 v32, v9, v9
	v_mul_f32_e32 v33, v11, v11
	v_fmac_f32_e32 v32, v8, v8
	v_fmac_f32_e32 v33, v10, v10
	v_add_f32_e32 v32, v32, v33
	v_add_f32_e32 v34, v34, v32
	v_mul_f32_e32 v32, v13, v13
	v_mul_f32_e32 v33, v15, v15
	v_fmac_f32_e32 v32, v12, v12
	v_fmac_f32_e32 v33, v14, v14
	v_add_f32_e32 v32, v32, v33
	v_add_f32_e32 v34, v34, v32
	ds_bpermute_b32 v32, v122, v34
	s_waitcnt lgkmcnt(0)
	v_add_f32_e32 v34, v34, v32
	ds_bpermute_b32 v32, v123, v34
	s_waitcnt lgkmcnt(0)
	v_add_f32_e32 v34, v34, v32
	ds_bpermute_b32 v32, v124, v34
	s_waitcnt lgkmcnt(0)
	v_add_f32_e32 v34, v34, v32
	ds_bpermute_b32 v32, v125, v34
	s_waitcnt lgkmcnt(0)
	v_add_f32_e32 v34, v34, v32
	ds_bpermute_b32 v32, v126, v34
	s_waitcnt lgkmcnt(0)
	v_add_f32_e32 v34, v34, v32
	ds_bpermute_b32 v32, v127, v34
	s_waitcnt lgkmcnt(0)
	v_add_f32_e32 v34, v34, v32
	v_fmamk_f32 v34, v34, 0x3a800000, v201
	v_cmp_gt_f32_e32 vcc, 0xf800000, v34
	v_mul_f32_e32 v32, 0x4f800000, v34
	s_nop 0
	v_cndmask_b32_e32 v34, v34, v32, vcc
	v_sqrt_f32_e32 v32, v34
	s_nop 0
	v_add_u32_e32 v35, -1, v32
	v_fma_f32 v36, -v35, v32, v34
	v_cmp_ge_f32_e64 s[38:39], 0, v36
	v_add_u32_e32 v36, 1, v32
	s_nop 0
	v_cndmask_b32_e64 v35, v32, v35, s[38:39]
	v_fma_f32 v32, -v36, v32, v34
	v_cmp_lt_f32_e64 s[38:39], 0, v32
	s_nop 1
	v_cndmask_b32_e64 v32, v35, v36, s[38:39]
	v_mul_f32_e32 v35, 0x37800000, v32
	v_cndmask_b32_e32 v32, v32, v35, vcc
	v_cmp_class_f32_e32 vcc, v34, v202
	s_nop 1
	v_cndmask_b32_e32 v34, v32, v34, vcc
	v_div_scale_f32 v32, s[38:39], v34, v34, 1.0
	v_rcp_f32_e32 v35, v32
	s_nop 0
	v_fma_f32 v36, -v32, v35, 1.0
	v_fmac_f32_e32 v35, v36, v35
	v_div_scale_f32 v36, vcc, 1.0, v34, 1.0
	v_mul_f32_e32 v37, v36, v35
	v_fma_f32 v178, -v32, v37, v36
	v_fmac_f32_e32 v37, v178, v35
	v_fma_f32 v32, -v32, v37, v36
	v_div_fmas_f32 v32, v32, v35, v37
	v_div_fixup_f32 v179, v32, v34, 1.0
	s_lshl_b32 s8, s101, 11
	s_add_u32 s12, s58, s8
	s_addc_u32 s13, s59, 0
	s_add_u32 s12, s12, 0x5500000
	s_addc_u32 s13, s13, 0
	s_waitcnt vmcnt(16)
	v_mul_f32_e32 v193, v0, v179
	v_add_f32_e32 v192, 1.0, v72
	v_mul_f32_e32 v193, v162, v193
	v_fma_f32 v180, v192, v193, v56
	v_mul_f32_e32 v193, v1, v179
	v_add_f32_e32 v192, 1.0, v73
	v_mul_f32_e32 v193, v163, v193
	v_fma_f32 v181, v192, v193, v57
	v_mul_f32_e32 v193, v2, v179
	v_add_f32_e32 v192, 1.0, v74
	v_mul_f32_e32 v193, v164, v193
	v_fma_f32 v182, v192, v193, v58
	v_mul_f32_e32 v193, v3, v179
	v_add_f32_e32 v192, 1.0, v75
	v_mul_f32_e32 v193, v165, v193
	v_fma_f32 v183, v192, v193, v59
	v_cvt_pk_bf16_f32 v184, v180, v181
	v_cvt_pk_bf16_f32 v185, v182, v183
	global_store_dwordx2 v121, v[184:185], s[12:13]
	v_mul_f32_e32 v193, v4, v179
	v_add_f32_e32 v192, 1.0, v76
	v_mul_f32_e32 v193, v166, v193
	v_fma_f32 v180, v192, v193, v60
	v_mul_f32_e32 v193, v5, v179
	v_add_f32_e32 v192, 1.0, v77
	v_mul_f32_e32 v193, v167, v193
	v_fma_f32 v181, v192, v193, v61
	v_mul_f32_e32 v193, v6, v179
	v_add_f32_e32 v192, 1.0, v78
	v_mul_f32_e32 v193, v168, v193
	v_fma_f32 v182, v192, v193, v62
	v_mul_f32_e32 v193, v7, v179
	v_add_f32_e32 v192, 1.0, v79
	v_mul_f32_e32 v193, v169, v193
	v_fma_f32 v183, v192, v193, v63
	v_cvt_pk_bf16_f32 v186, v180, v181
	v_cvt_pk_bf16_f32 v187, v182, v183
	global_store_dwordx2 v121, v[186:187], s[12:13] offset:512
	v_mul_f32_e32 v193, v8, v179
	v_add_f32_e32 v192, 1.0, v80
	v_mul_f32_e32 v193, v170, v193
	v_fma_f32 v180, v192, v193, v64
	v_mul_f32_e32 v193, v9, v179
	v_add_f32_e32 v192, 1.0, v81
	v_mul_f32_e32 v193, v171, v193
	v_fma_f32 v181, v192, v193, v65
	v_mul_f32_e32 v193, v10, v179
	v_add_f32_e32 v192, 1.0, v82
	v_mul_f32_e32 v193, v172, v193
	v_fma_f32 v182, v192, v193, v66
	v_mul_f32_e32 v193, v11, v179
	v_add_f32_e32 v192, 1.0, v83
	v_mul_f32_e32 v193, v173, v193
	v_fma_f32 v183, v192, v193, v67
	v_cvt_pk_bf16_f32 v188, v180, v181
	v_cvt_pk_bf16_f32 v189, v182, v183
	global_store_dwordx2 v121, v[188:189], s[12:13] offset:1024
	v_mul_f32_e32 v193, v12, v179
	v_add_f32_e32 v192, 1.0, v84
	v_mul_f32_e32 v193, v174, v193
	v_fma_f32 v180, v192, v193, v68
	v_mul_f32_e32 v193, v13, v179
	v_add_f32_e32 v192, 1.0, v85
	v_mul_f32_e32 v193, v175, v193
	v_fma_f32 v181, v192, v193, v69
	v_mul_f32_e32 v193, v14, v179
	v_add_f32_e32 v192, 1.0, v86
	v_mul_f32_e32 v193, v176, v193
	v_fma_f32 v182, v192, v193, v70
	v_mul_f32_e32 v193, v15, v179
	v_add_f32_e32 v192, 1.0, v87
	v_mul_f32_e32 v193, v177, v193
	v_fma_f32 v183, v192, v193, v71
	v_cvt_pk_bf16_f32 v190, v180, v181
	v_cvt_pk_bf16_f32 v191, v182, v183
	global_store_dwordx2 v121, v[190:191], s[12:13] offset:1536
	s_mul_i32 s100, s68, 3
	s_add_u32 s100, s100, s101
	s_cmp_le_u32 s100, s71
	s_cselect_b32 s100, s100, s101
	s_lshr_b32 s8, s100, 8
	s_mul_i32 s8, s8, 57
	s_lshr_b32 s8, s8, 9
	s_mul_i32 s9, s8, 0x900
	s_sub_u32 s9, s100, s9
	s_lshl_b32 s12, s8, 11
	s_add_u32 s12, s12, s9
	s_sub_u32 s12, s12, 0x100
	s_lshl_b32 s8, s8, 8
	s_add_u32 s8, s8, s9
	s_cmp_lt_u32 s9, 0x100
	s_cselect_b32 s8, s8, s12
	s_cselect_b32 s12, s36, s56
	s_cselect_b32 s13, s37, s57
	s_lshl_b32 s8, s8, 12
	s_add_u32 s12, s12, s8
	s_addc_u32 s13, s13, 0
	global_load_dwordx4 v[0:3], v120, s[12:13]
	global_load_dwordx4 v[4:7], v120, s[12:13] offset:1024
	global_load_dwordx4 v[8:11], v120, s[12:13] offset:2048
	global_load_dwordx4 v[12:15], v120, s[12:13] offset:3072
	s_add_u32 s101, s101, s68
	s_cmp_gt_u32 s101, s71
	s_cbranch_scc1 .Lnf_n1_exit
; __device__ __forceinline__ unsigned pk2(float lo, float hi) { f32x2_t v = {lo, hi}; bf16x2_t b = __builtin_convertvector(v, bf16x2_t); return __builtin_bit_cast(unsigned, b); }
; __device__ __forceinline__ void phase_norm(const Params& P, int l, int which, bool first) {
;     ...
;     for (int r = gw; r < ROWS; r += NGW) {
;         const int b = r / TT, t = r - b * TT; const int bb = (t < CTX) ? 16 : b;
;         float* xr = xrow_ptr(P, r);
;         const float* src = first ? ((t < CTX) ? P.ctx + ((size_t)b * CTX + t) * DM : P.x + ((size_t)b * SEQ + (t - CTX)) * DM) : xr;
;         f32x4 v[4]; float s2 = 0.f;
; #pragma unroll
;         for (int j = 0; j < 4; ++j) { v[j] = *((const f32x4*)src + lane + 64 * j); s2 += (v[j].x * v[j].x + v[j].y * v[j].y) + (v[j].z * v[j].z + v[j].w * v[j].w); }
;         if (first) {
; #pragma unroll
;             for (int j = 0; j < 4; ++j) *((f32x4*)xr + lane + 64 * j) = v[j];
;         }
;         const float rstd = 1.0f / sqrtf(wave_sum(s2, lane) * (1.0f / DM) + RMS_EPS);
;         const float* mrow = mod + (size_t)bb * MODW;
; #pragma unroll
;         for (int j = 0; j < 4; ++j) {
;             const int c0 = 4 * (lane + 64 * j);
;             const f32x4 g = *(const f32x4*)(gain + c0), sh = *(const f32x4*)(mrow + c0), scl = *(const f32x4*)(mrow + DM + c0);
;             const f32x4 y = v[j] * rstd * g * (scl + 1.0f) + sh;
;             u32x2 w; w.x = pk2(y.x, y.y); w.y = pk2(y.z, y.w);
;             *(u32x2*)(H + (size_t)r * DM + c0) = w;
;         }
;     }
	s_waitcnt vmcnt(32)
	s_add_u32 s100, s101, s68
	s_cmp_le_u32 s100, s71
	s_cselect_b32 s100, s100, s101
	s_lshr_b32 s8, s100, 8
	s_mul_i32 s8, s8, 57
	s_lshr_b32 s8, s8, 9
	s_mul_i32 s9, s8, 0x900
	s_sub_u32 s9, s100, s9
	s_cmp_lt_u32 s9, 0x100
	s_cselect_b32 s8, 16, s8
	s_mul_i32 s8, s8, 0x6000
	s_add_u32 s12, s50, s8
	s_addc_u32 s13, s51, 0
	global_load_dwordx4 v[130:133], v120, s[12:13] offset:-4096
	global_load_dwordx4 v[134:137], v120, s[12:13] offset:-3072
	global_load_dwordx4 v[138:141], v120, s[12:13] offset:-2048
	global_load_dwordx4 v[142:145], v120, s[12:13] offset:-1024
	global_load_dwordx4 v[146:149], v120, s[12:13]
	global_load_dwordx4 v[150:153], v120, s[12:13] offset:1024
	global_load_dwordx4 v[154:157], v120, s[12:13] offset:2048
	global_load_dwordx4 v[158:161], v120, s[12:13] offset:3072
	v_mul_f32_e32 v32, v17, v17
	v_mul_f32_e32 v33, v19, v19
	v_fmac_f32_e32 v32, v16, v16
	v_fmac_f32_e32 v33, v18, v18
	v_add_f32_e32 v34, v32, v33
	v_mul_f32_e32 v32, v21, v21
	v_mul_f32_e32 v33, v23, v23
	v_fmac_f32_e32 v32, v20, v20
	v_fmac_f32_e32 v33, v22, v22
	v_add_f32_e32 v32, v32, v33
	v_add_f32_e32 v34, v34, v32
	v_mul_f32_e32 v32, v25, v25
	v_mul_f32_e32 v33, v27, v27
	v_fmac_f32_e32 v32, v24, v24
	v_fmac_f32_e32 v33, v26, v26
	v_add_f32_e32 v32, v32, v33
	v_add_f32_e32 v34, v34, v32
	v_mul_f32_e32 v32, v29, v29
	v_mul_f32_e32 v33, v31, v31
	v_fmac_f32_e32 v32, v28, v28
	v_fmac_f32_e32 v33, v30, v30
	v_add_f32_e32 v32, v32, v33
	v_add_f32_e32 v34, v34, v32
	ds_bpermute_b32 v32, v122, v34
	s_waitcnt lgkmcnt(0)
	v_add_f32_e32 v34, v34, v32
	ds_bpermute_b32 v32, v123, v34
	s_waitcnt lgkmcnt(0)
	v_add_f32_e32 v34, v34, v32
	ds_bpermute_b32 v32, v124, v34
	s_waitcnt lgkmcnt(0)
	v_add_f32_e32 v34, v34, v32
	ds_bpermute_b32 v32, v125, v34
	s_waitcnt lgkmcnt(0)
	v_add_f32_e32 v34, v34, v32
	ds_bpermute_b32 v32, v126, v34
	s_waitcnt lgkmcnt(0)
	v_add_f32_e32 v34, v34, v32
	ds_bpermute_b32 v32, v127, v34
	s_waitcnt lgkmcnt(0)
	v_add_f32_e32 v34, v34, v32
	v_fmamk_f32 v34, v34, 0x3a800000, v201
	v_cmp_gt_f32_e32 vcc, 0xf800000, v34
	v_mul_f32_e32 v32, 0x4f800000, v34
	s_nop 0
	v_cndmask_b32_e32 v34, v34, v32, vcc
	v_sqrt_f32_e32 v32, v34
	s_nop 0
	v_add_u32_e32 v35, -1, v32
	v_fma_f32 v36, -v35, v32, v34
	v_cmp_ge_f32_e64 s[38:39], 0, v36
	v_add_u32_e32 v36, 1, v32
	s_nop 0
	v_cndmask_b32_e64 v35, v32, v35, s[38:39]
	v_fma_f32 v32, -v36, v32, v34
	v_cmp_lt_f32_e64 s[38:39], 0, v32
	s_nop 1
	v_cndmask_b32_e64 v32, v35, v36, s[38:39]
	v_mul_f32_e32 v35, 0x37800000, v32
	v_cndmask_b32_e32 v32, v32, v35, vcc
	v_cmp_class_f32_e32 vcc, v34, v202
	s_nop 1
	v_cndmask_b32_e32 v34, v32, v34, vcc
	v_div_scale_f32 v32, s[38:39], v34, v34, 1.0
	v_rcp_f32_e32 v35, v32
	s_nop 0
	v_fma_f32 v36, -v32, v35, 1.0
	v_fmac_f32_e32 v35, v36, v35
	v_div_scale_f32 v36, vcc, 1.0, v34, 1.0
	v_mul_f32_e32 v37, v36, v35
	v_fma_f32 v178, -v32, v37, v36
	v_fmac_f32_e32 v37, v178, v35
	v_fma_f32 v32, -v32, v37, v36
	v_div_fmas_f32 v32, v32, v35, v37
	v_div_fixup_f32 v179, v32, v34, 1.0
	s_lshl_b32 s8, s101, 11
	s_add_u32 s12, s58, s8
	s_addc_u32 s13, s59, 0
	s_add_u32 s12, s12, 0x5500000
	s_addc_u32 s13, s13, 0
	s_waitcnt vmcnt(16)
	v_mul_f32_e32 v193, v16, v179
	v_add_f32_e32 v192, 1.0, v104
	v_mul_f32_e32 v193, v162, v193
	v_fma_f32 v180, v192, v193, v88
	v_mul_f32_e32 v193, v17, v179
	v_add_f32_e32 v192, 1.0, v105
	v_mul_f32_e32 v193, v163, v193
	v_fma_f32 v181, v192, v193, v89
	v_mul_f32_e32 v193, v18, v179
	v_add_f32_e32 v192, 1.0, v106
	v_mul_f32_e32 v193, v164, v193
	v_fma_f32 v182, v192, v193, v90
	v_mul_f32_e32 v193, v19, v179
	v_add_f32_e32 v192, 1.0, v107
	v_mul_f32_e32 v193, v165, v193
	v_fma_f32 v183, v192, v193, v91
	v_cvt_pk_bf16_f32 v184, v180, v181
	v_cvt_pk_bf16_f32 v185, v182, v183
	global_store_dwordx2 v121, v[184:185], s[12:13]
	v_mul_f32_e32 v193, v20, v179
	v_add_f32_e32 v192, 1.0, v108
	v_mul_f32_e32 v193, v166, v193
	v_fma_f32 v180, v192, v193, v92
	v_mul_f32_e32 v193, v21, v179
	v_add_f32_e32 v192, 1.0, v109
	v_mul_f32_e32 v193, v167, v193
	v_fma_f32 v181, v192, v193, v93
	v_mul_f32_e32 v193, v22, v179
	v_add_f32_e32 v192, 1.0, v110
	v_mul_f32_e32 v193, v168, v193
	v_fma_f32 v182, v192, v193, v94
	v_mul_f32_e32 v193, v23, v179
	v_add_f32_e32 v192, 1.0, v111
	v_mul_f32_e32 v193, v169, v193
	v_fma_f32 v183, v192, v193, v95
	v_cvt_pk_bf16_f32 v186, v180, v181
	v_cvt_pk_bf16_f32 v187, v182, v183
	global_store_dwordx2 v121, v[186:187], s[12:13] offset:512
	v_mul_f32_e32 v193, v24, v179
	v_add_f32_e32 v192, 1.0, v112
	v_mul_f32_e32 v193, v170, v193
	v_fma_f32 v180, v192, v193, v96
	v_mul_f32_e32 v193, v25, v179
	v_add_f32_e32 v192, 1.0, v113
	v_mul_f32_e32 v193, v171, v193
	v_fma_f32 v181, v192, v193, v97
	v_mul_f32_e32 v193, v26, v179
	v_add_f32_e32 v192, 1.0, v114
	v_mul_f32_e32 v193, v172, v193
	v_fma_f32 v182, v192, v193, v98
	v_mul_f32_e32 v193, v27, v179
	v_add_f32_e32 v192, 1.0, v115
	v_mul_f32_e32 v193, v173, v193
	v_fma_f32 v183, v192, v193, v99
	v_cvt_pk_bf16_f32 v188, v180, v181
	v_cvt_pk_bf16_f32 v189, v182, v183
	global_store_dwordx2 v121, v[188:189], s[12:13] offset:1024
	v_mul_f32_e32 v193, v28, v179
	v_add_f32_e32 v192, 1.0, v116
	v_mul_f32_e32 v193, v174, v193
	v_fma_f32 v180, v192, v193, v100
	v_mul_f32_e32 v193, v29, v179
	v_add_f32_e32 v192, 1.0, v117
	v_mul_f32_e32 v193, v175, v193
	v_fma_f32 v181, v192, v193, v101
	v_mul_f32_e32 v193, v30, v179
	v_add_f32_e32 v192, 1.0, v118
	v_mul_f32_e32 v193, v176, v193
	v_fma_f32 v182, v192, v193, v102
	v_mul_f32_e32 v193, v31, v179
	v_add_f32_e32 v192, 1.0, v119
	v_mul_f32_e32 v193, v177, v193
	v_fma_f32 v183, v192, v193, v103
	v_cvt_pk_bf16_f32 v190, v180, v181
	v_cvt_pk_bf16_f32 v191, v182, v183
	global_store_dwordx2 v121, v[190:191], s[12:13] offset:1536
	s_mul_i32 s100, s68, 3
	s_add_u32 s100, s100, s101
	s_cmp_le_u32 s100, s71
	s_cselect_b32 s100, s100, s101
	s_lshr_b32 s8, s100, 8
	s_mul_i32 s8, s8, 57
	s_lshr_b32 s8, s8, 9
	s_mul_i32 s9, s8, 0x900
	s_sub_u32 s9, s100, s9
	s_lshl_b32 s12, s8, 11
	s_add_u32 s12, s12, s9
	s_sub_u32 s12, s12, 0x100
	s_lshl_b32 s8, s8, 8
	s_add_u32 s8, s8, s9
	s_cmp_lt_u32 s9, 0x100
	s_cselect_b32 s8, s8, s12
	s_cselect_b32 s12, s36, s56
	s_cselect_b32 s13, s37, s57
	s_lshl_b32 s8, s8, 12
	s_add_u32 s12, s12, s8
	s_addc_u32 s13, s13, 0
	global_load_dwordx4 v[16:19], v120, s[12:13]
	global_load_dwordx4 v[20:23], v120, s[12:13] offset:1024
	global_load_dwordx4 v[24:27], v120, s[12:13] offset:2048
	global_load_dwordx4 v[28:31], v120, s[12:13] offset:3072
	s_add_u32 s101, s101, s68
	s_cmp_gt_u32 s101, s71
	s_cbranch_scc1 .Lnf_n1_exit
; __device__ __forceinline__ unsigned pk2(float lo, float hi) { f32x2_t v = {lo, hi}; bf16x2_t b = __builtin_convertvector(v, bf16x2_t); return __builtin_bit_cast(unsigned, b); }
; __device__ __forceinline__ void phase_norm(const Params& P, int l, int which, bool first) {
;     ...
;     for (int r = gw; r < ROWS; r += NGW) {
;         const int b = r / TT, t = r - b * TT; const int bb = (t < CTX) ? 16 : b;
;         float* xr = xrow_ptr(P, r);
;         const float* src = first ? ((t < CTX) ? P.ctx + ((size_t)b * CTX + t) * DM : P.x + ((size_t)b * SEQ + (t - CTX)) * DM) : xr;
;         f32x4 v[4]; float s2 = 0.f;
; #pragma unroll
;         for (int j = 0; j < 4; ++j) { v[j] = *((const f32x4*)src + lane + 64 * j); s2 += (v[j].x * v[j].x + v[j].y * v[j].y) + (v[j].z * v[j].z + v[j].w * v[j].w); }
;         if (first) {
; #pragma unroll
;             for (int j = 0; j < 4; ++j) *((f32x4*)xr + lane + 64 * j) = v[j];
;         }
;         const float rstd = 1.0f / sqrtf(wave_sum(s2, lane) * (1.0f / DM) + RMS_EPS);
;         const float* mrow = mod + (size_t)bb * MODW;
; #pragma unroll
;         for (int j = 0; j < 4; ++j) {
;             const int c0 = 4 * (lane + 64 * j);
;             const f32x4 g = *(const f32x4*)(gain + c0), sh = *(const f32x4*)(mrow + c0), scl = *(const f32x4*)(mrow + DM + c0);
;             const f32x4 y = v[j] * rstd * g * (scl + 1.0f) + sh;
;             u32x2 w; w.x = pk2(y.x, y.y); w.y = pk2(y.z, y.w);
;             *(u32x2*)(H + (size_t)r * DM + c0) = w;
;         }
;     }
	s_waitcnt vmcnt(32)
	s_add_u32 s100, s101, s68
	s_cmp_le_u32 s100, s71
	s_cselect_b32 s100, s100, s101
	s_lshr_b32 s8, s100, 8
	s_mul_i32 s8, s8, 57
	s_lshr_b32 s8, s8, 9
	s_mul_i32 s9, s8, 0x900
	s_sub_u32 s9, s100, s9
	s_cmp_lt_u32 s9, 0x100
	s_cselect_b32 s8, 16, s8
	s_mul_i32 s8, s8, 0x6000
	s_add_u32 s12, s50, s8
	s_addc_u32 s13, s51, 0
	global_load_dwordx4 v[56:59], v120, s[12:13] offset:-4096
	global_load_dwordx4 v[60:63], v120, s[12:13] offset:-3072
	global_load_dwordx4 v[64:67], v120, s[12:13] offset:-2048
	global_load_dwordx4 v[68:71], v120, s[12:13] offset:-1024
	global_load_dwordx4 v[72:75], v120, s[12:13]
	global_load_dwordx4 v[76:79], v120, s[12:13] offset:1024
	global_load_dwordx4 v[80:83], v120, s[12:13] offset:2048
	global_load_dwordx4 v[84:87], v120, s[12:13] offset:3072
	v_mul_f32_e32 v32, v41, v41
	v_mul_f32_e32 v33, v43, v43
	v_fmac_f32_e32 v32, v40, v40
	v_fmac_f32_e32 v33, v42, v42
	v_add_f32_e32 v34, v32, v33
	v_mul_f32_e32 v32, v45, v45
	v_mul_f32_e32 v33, v47, v47
	v_fmac_f32_e32 v32, v44, v44
	v_fmac_f32_e32 v33, v46, v46
	v_add_f32_e32 v32, v32, v33
	v_add_f32_e32 v34, v34, v32
	v_mul_f32_e32 v32, v49, v49
	v_mul_f32_e32 v33, v51, v51
	v_fmac_f32_e32 v32, v48, v48
	v_fmac_f32_e32 v33, v50, v50
	v_add_f32_e32 v32, v32, v33
	v_add_f32_e32 v34, v34, v32
	v_mul_f32_e32 v32, v53, v53
	v_mul_f32_e32 v33, v55, v55
	v_fmac_f32_e32 v32, v52, v52
	v_fmac_f32_e32 v33, v54, v54
	v_add_f32_e32 v32, v32, v33
	v_add_f32_e32 v34, v34, v32
	ds_bpermute_b32 v32, v122, v34
	s_waitcnt lgkmcnt(0)
	v_add_f32_e32 v34, v34, v32
	ds_bpermute_b32 v32, v123, v34
	s_waitcnt lgkmcnt(0)
	v_add_f32_e32 v34, v34, v32
	ds_bpermute_b32 v32, v124, v34
	s_waitcnt lgkmcnt(0)
	v_add_f32_e32 v34, v34, v32
	ds_bpermute_b32 v32, v125, v34
	s_waitcnt lgkmcnt(0)
	v_add_f32_e32 v34, v34, v32
	ds_bpermute_b32 v32, v126, v34
	s_waitcnt lgkmcnt(0)
	v_add_f32_e32 v34, v34, v32
	ds_bpermute_b32 v32, v127, v34
	s_waitcnt lgkmcnt(0)
	v_add_f32_e32 v34, v34, v32
	v_fmamk_f32 v34, v34, 0x3a800000, v201
	v_cmp_gt_f32_e32 vcc, 0xf800000, v34
	v_mul_f32_e32 v32, 0x4f800000, v34
	s_nop 0
	v_cndmask_b32_e32 v34, v34, v32, vcc
	v_sqrt_f32_e32 v32, v34
	s_nop 0
	v_add_u32_e32 v35, -1, v32
	v_fma_f32 v36, -v35, v32, v34
	v_cmp_ge_f32_e64 s[38:39], 0, v36
	v_add_u32_e32 v36, 1, v32
	s_nop 0
	v_cndmask_b32_e64 v35, v32, v35, s[38:39]
	v_fma_f32 v32, -v36, v32, v34
	v_cmp_lt_f32_e64 s[38:39], 0, v32
	s_nop 1
	v_cndmask_b32_e64 v32, v35, v36, s[38:39]
	v_mul_f32_e32 v35, 0x37800000, v32
	v_cndmask_b32_e32 v32, v32, v35, vcc
	v_cmp_class_f32_e32 vcc, v34, v202
	s_nop 1
	v_cndmask_b32_e32 v34, v32, v34, vcc
	v_div_scale_f32 v32, s[38:39], v34, v34, 1.0
	v_rcp_f32_e32 v35, v32
	s_nop 0
	v_fma_f32 v36, -v32, v35, 1.0
	v_fmac_f32_e32 v35, v36, v35
	v_div_scale_f32 v36, vcc, 1.0, v34, 1.0
	v_mul_f32_e32 v37, v36, v35
	v_fma_f32 v178, -v32, v37, v36
	v_fmac_f32_e32 v37, v178, v35
	v_fma_f32 v32, -v32, v37, v36
	v_div_fmas_f32 v32, v32, v35, v37
	v_div_fixup_f32 v179, v32, v34, 1.0
	s_lshl_b32 s8, s101, 11
	s_add_u32 s12, s58, s8
	s_addc_u32 s13, s59, 0
	s_add_u32 s12, s12, 0x5500000
	s_addc_u32 s13, s13, 0
	s_waitcnt vmcnt(16)
	v_mul_f32_e32 v193, v40, v179
	v_add_f32_e32 v192, 1.0, v146
	v_mul_f32_e32 v193, v162, v193
	v_fma_f32 v180, v192, v193, v130
	v_mul_f32_e32 v193, v41, v179
	v_add_f32_e32 v192, 1.0, v147
	v_mul_f32_e32 v193, v163, v193
	v_fma_f32 v181, v192, v193, v131
	v_mul_f32_e32 v193, v42, v179
	v_add_f32_e32 v192, 1.0, v148
	v_mul_f32_e32 v193, v164, v193
	v_fma_f32 v182, v192, v193, v132
	v_mul_f32_e32 v193, v43, v179
	v_add_f32_e32 v192, 1.0, v149
	v_mul_f32_e32 v193, v165, v193
	v_fma_f32 v183, v192, v193, v133
	v_cvt_pk_bf16_f32 v184, v180, v181
	v_cvt_pk_bf16_f32 v185, v182, v183
	global_store_dwordx2 v121, v[184:185], s[12:13]
	v_mul_f32_e32 v193, v44, v179
	v_add_f32_e32 v192, 1.0, v150
	v_mul_f32_e32 v193, v166, v193
	v_fma_f32 v180, v192, v193, v134
	v_mul_f32_e32 v193, v45, v179
	v_add_f32_e32 v192, 1.0, v151
	v_mul_f32_e32 v193, v167, v193
	v_fma_f32 v181, v192, v193, v135
	v_mul_f32_e32 v193, v46, v179
	v_add_f32_e32 v192, 1.0, v152
	v_mul_f32_e32 v193, v168, v193
	v_fma_f32 v182, v192, v193, v136
	v_mul_f32_e32 v193, v47, v179
	v_add_f32_e32 v192, 1.0, v153
	v_mul_f32_e32 v193, v169, v193
	v_fma_f32 v183, v192, v193, v137
	v_cvt_pk_bf16_f32 v186, v180, v181
	v_cvt_pk_bf16_f32 v187, v182, v183
	global_store_dwordx2 v121, v[186:187], s[12:13] offset:512
	v_mul_f32_e32 v193, v48, v179
	v_add_f32_e32 v192, 1.0, v154
	v_mul_f32_e32 v193, v170, v193
	v_fma_f32 v180, v192, v193, v138
	v_mul_f32_e32 v193, v49, v179
	v_add_f32_e32 v192, 1.0, v155
	v_mul_f32_e32 v193, v171, v193
	v_fma_f32 v181, v192, v193, v139
	v_mul_f32_e32 v193, v50, v179
	v_add_f32_e32 v192, 1.0, v156
	v_mul_f32_e32 v193, v172, v193
	v_fma_f32 v182, v192, v193, v140
	v_mul_f32_e32 v193, v51, v179
	v_add_f32_e32 v192, 1.0, v157
	v_mul_f32_e32 v193, v173, v193
	v_fma_f32 v183, v192, v193, v141
	v_cvt_pk_bf16_f32 v188, v180, v181
	v_cvt_pk_bf16_f32 v189, v182, v183
	global_store_dwordx2 v121, v[188:189], s[12:13] offset:1024
	v_mul_f32_e32 v193, v52, v179
	v_add_f32_e32 v192, 1.0, v158
	v_mul_f32_e32 v193, v174, v193
	v_fma_f32 v180, v192, v193, v142
	v_mul_f32_e32 v193, v53, v179
	v_add_f32_e32 v192, 1.0, v159
	v_mul_f32_e32 v193, v175, v193
	v_fma_f32 v181, v192, v193, v143
	v_mul_f32_e32 v193, v54, v179
	v_add_f32_e32 v192, 1.0, v160
	v_mul_f32_e32 v193, v176, v193
	v_fma_f32 v182, v192, v193, v144
	v_mul_f32_e32 v193, v55, v179
	v_add_f32_e32 v192, 1.0, v161
	v_mul_f32_e32 v193, v177, v193
	v_fma_f32 v183, v192, v193, v145
	v_cvt_pk_bf16_f32 v190, v180, v181
	v_cvt_pk_bf16_f32 v191, v182, v183
	global_store_dwordx2 v121, v[190:191], s[12:13] offset:1536
	s_mul_i32 s100, s68, 3
	s_add_u32 s100, s100, s101
	s_cmp_le_u32 s100, s71
	s_cselect_b32 s100, s100, s101
	s_lshr_b32 s8, s100, 8
	s_mul_i32 s8, s8, 57
	s_lshr_b32 s8, s8, 9
	s_mul_i32 s9, s8, 0x900
	s_sub_u32 s9, s100, s9
	s_lshl_b32 s12, s8, 11
	s_add_u32 s12, s12, s9
	s_sub_u32 s12, s12, 0x100
	s_lshl_b32 s8, s8, 8
	s_add_u32 s8, s8, s9
	s_cmp_lt_u32 s9, 0x100
	s_cselect_b32 s8, s8, s12
	s_cselect_b32 s12, s36, s56
	s_cselect_b32 s13, s37, s57
	s_lshl_b32 s8, s8, 12
	s_add_u32 s12, s12, s8
	s_addc_u32 s13, s13, 0
	global_load_dwordx4 v[40:43], v120, s[12:13]
	global_load_dwordx4 v[44:47], v120, s[12:13] offset:1024
	global_load_dwordx4 v[48:51], v120, s[12:13] offset:2048
	global_load_dwordx4 v[52:55], v120, s[12:13] offset:3072
	s_add_u32 s101, s101, s68
	s_cmp_gt_u32 s101, s71
	s_cbranch_scc1 .Lnf_n1_exit
	s_branch .Lnf_n1_loop
; __device__ __forceinline__ int opaque_tid() { int t = threadIdx.x; asm volatile("" : "+v"(t)); return t; }
; __device__ __forceinline__ void phase_norm(const Params& P, int l, int which, bool first) {
;     const int tid = opaque_tid(), lane = tid & 63, wave = tid >> 6;
;     const int gw = blockIdx.x * 8 + wave, NGW = gridDim.x * 8;
;     const float* gain = (which == 0 ? P.norm1 : P.norm2) + (size_t)l * DM;
;     const float* mod = (const float*)(P.ws + WS_MOD) + (size_t)l * 17 * MODW + (which == 0 ? 0 : 3 * DM);
;     bf16_t* H = (bf16_t*)(P.ws + WS_H);
;     for (int r = gw; r < ROWS; r += NGW) {
;         const int b = r / TT, t = r - b * TT; const int bb = (t < CTX) ? 16 : b;
;         float* xr = xrow_ptr(P, r);
;         const float* src = first ? ((t < CTX) ? P.ctx + ((size_t)b * CTX + t) * DM : P.x + ((size_t)b * SEQ + (t - CTX)) * DM) : xr;
;         f32x4 v[4]; float s2 = 0.f;
; #pragma unroll
;         for (int j = 0; j < 4; ++j) { v[j] = *((const f32x4*)src + lane + 64 * j); s2 += (v[j].x * v[j].x + v[j].y * v[j].y) + (v[j].z * v[j].z + v[j].w * v[j].w); }
;         if (first) {
; #pragma unroll
;             for (int j = 0; j < 4; ++j) *((f32x4*)xr + lane + 64 * j) = v[j];
;         }
;         const float rstd = 1.0f / sqrtf(wave_sum(s2, lane) * (1.0f / DM) + RMS_EPS);
.Lnf_n1_exit:
	s_waitcnt vmcnt(0)
	s_branch .LBB0_75
.Lnf_n1_orig:
	v_readlane_b32 s8, v255, 2
	s_waitcnt lgkmcnt(0)
	s_add_u32 s8, s58, s8
	v_readlane_b32 s9, v254, 63
	s_addc_u32 s9, s59, s9
	s_add_u32 s50, s8, 0x100000
	s_addc_u32 s51, s9, 0
	v_readlane_b32 s8, v255, 0
	v_readlane_b32 s9, v255, 1
	s_lshl_b64 s[8:9], s[8:9], 12
	s_load_dwordx2 s[36:37], s[38:39], 0x0
	s_load_dwordx2 s[48:49], s[38:39], 0x10
	s_add_u32 s8, s44, s8
	v_and_b32_e32 v0, 63, v0
	v_ashrrev_i32_e32 v17, 31, v16
	s_addc_u32 s9, s45, s9
	v_lshlrev_b32_e32 v128, 4, v0
	v_lshlrev_b64 v[10:11], 11, v[16:17]
	v_lshlrev_b32_e32 v2, 2, v0
	v_lshl_add_u64 v[18:19], s[8:9], 0, v[128:129]
	s_add_u32 s8, s58, 0x4500000
	v_lshl_or_b32 v10, v0, 3, v10
	v_or_b32_e32 v4, 0x100, v2
	v_or_b32_e32 v6, 0x200, v2
	v_or_b32_e32 v8, 0x300, v2
	s_addc_u32 s9, s59, 0
	v_lshl_add_u64 v[10:11], s[58:59], 0, v[10:11]
	s_mov_b64 s[12:13], 0x5500000
	v_lshlrev_b32_e32 v22, 4, v0
	v_xor_b32_e32 v39, 4, v2
	v_xor_b32_e32 v40, 8, v2
	v_xor_b32_e32 v41, 16, v2
	v_xor_b32_e32 v42, 32, v2
	v_xor_b32_e32 v43, 64, v2
	v_xor_b32_e32 v44, 0x80, v2
	v_lshl_add_u64 v[20:21], v[10:11], 0, s[12:13]
	s_mov_b64 s[44:45], 0
	v_mov_b32_e32 v17, s57
	v_mov_b32_e32 v45, s9
	v_mov_b32_e32 v46, s56
	v_mov_b32_e32 v47, s8
	v_mov_b32_e32 v24, v22
	v_mov_b32_e32 v25, v129
	v_lshlrev_b32_e32 v26, 2, v2
	v_lshlrev_b32_e32 v28, 2, v4
	v_lshlrev_b32_e32 v30, 2, v6
	v_lshlrev_b32_e32 v32, 2, v8
	s_branch .LBB0_67
